# mixers queue order: memory-attention / spatial-gate units first, the short retention-sample units last (shorter phase tail)
# speedup vs baseline: 1.0053x; 1.0040x over previous
; #define LAS __attribute__((address_space(3)))
; __device__ __forceinline__ f32x4 unpack4(u32x2 u) { f32x4 r; r[0] = bflo(u[0]); r[1] = bfhi(u[0]); r[2] = bflo(u[1]); r[3] = bfhi(u[1]); return r; }
; __device__ __forceinline__ void mix_sg_sample(const Params& p, LAS unsigned char* lds, int b) {
;   int tid = threadIdx.x; asm volatile("" : "+v"(tid)); const int w = tid >> 6, lane = tid & 63;
;   unsigned char* ws = p.ws;
;   const bf16_t* VA = (const bf16_t*)(ws + WS_VA); const bf16_t* U = (const bf16_t*)(ws + WS_U);
;   bf16_t* ACAT = (bf16_t*)(ws + WS_ACAT);
;   LAS float* vs = (LAS float*)lds;
;   const int r0 = TOKP + 8 * b;
;   __syncthreads();
; #pragma unroll
;   for (int g = 0; g < 4; ++g) {
;     const int col = g * 256 + 4 * lane;
;     const f32x4 x = unpack4(*(const u32x2*)(VA + (size_t)(r0 + w) * 1024 + col));
;     const float mean = wave_sum(x[0] + x[1] + x[2] + x[3]) * (1.0f / 256.0f);
;     const f32x4 d = x - mean;
;     const float var = wave_sum(d[0] * d[0] + d[1] * d[1] + d[2] * d[2] + d[3] * d[3]) * (1.0f / 256.0f);
;     const float rstd = rsqrtf(var + LN_EPS);
;     const f32x4 gg = *(const f32x4*)(p.in[7] + col), bb = *(const f32x4*)(p.in[8] + col);
;     const f32x4 va = d * rstd * gg + bb;
;     *(f32x4*)(p.out + O_CV + (size_t)(b * 8 + w) * 1024 + col) = va;
;     *(LAS f32x4*)(vs + w * 1024 + col) = va;
;   }
; __device__ __forceinline__ void phase_mixers(const Params& p, LAS unsigned char* lds, int rep) {
;     ...
;     const int u = (int)__builtin_amdgcn_readfirstlane(*slot);
;     if (u >= 2304) break;
;     if (threadIdx.x == 0) nxt = atomicAdd(ctr, 1u);
;     if (u < 128) mix_ret_prompt(p, lds, u);
;     else {
;       const int v = u - 128, g = v / 17, s = v % 17;
;       if (s < 8) mix_ret_sample(p, lds, g * 8 + s);
;       else if (s < 12) mix_ma_sample(p, lds, g * 4 + (s - 8));
;       else if (s < 14) mix_ma_prompt(p, lds, g * 2 + (s - 12));
;       else if (s < 16) mix_sg_prompt(p, lds, g * 2 + (s - 14));
;       else mix_sg_sample(p, lds, g);
.LBB0_193:
	s_add_i32 s29, s42, 0xff80
	s_and_b32 s29, s29, 0xffff
	s_cmpk_lt_u32 s29, 0x480
	s_cbranch_scc0 .Lq_late
	s_mul_i32 s34, s29, 0x1c72
	s_lshr_b32 s34, s34, 16
	s_mul_i32 s35, s34, 9
	s_sub_i32 s35, s29, s35
	s_mul_i32 s34, s34, 17
	s_add_i32 s29, s34, s35
	s_add_i32 s29, s29, 8
	s_branch .Lq_done
.Lq_late:
	s_sub_i32 s29, s29, 0x480
	s_lshr_b32 s34, s29, 3
	s_and_b32 s35, s29, 7
	s_mul_i32 s34, s34, 17
	s_add_i32 s29, s34, s35
.Lq_done:
	s_and_b32 s34, s29, 0xffff
	s_mul_i32 s34, s34, 0xf0f1
	s_lshr_b32 s44, s34, 20
	s_mul_i32 s34, s44, 17
	s_sub_i32 s29, s29, s34
	s_and_b32 s43, s29, 0xffff
	s_cmp_gt_u32 s43, 7
	s_cbranch_scc0 .LBB0_232
	s_cmp_gt_u32 s43, 11
	s_cbranch_scc0 .LBB0_219
	s_cmp_gt_u32 s43, 13
	s_cbranch_scc0 .LBB0_216
	s_cmp_gt_u32 s43, 15
	s_cbranch_scc0 .LBB0_214
	v_and_b32_e32 v1, 64, v230
	v_add_u32_e32 v1, 64, v1
	v_xor_b32_e32 v4, 32, v230
	v_cmp_lt_i32_e32 vcc, v4, v1
	v_mov_b32_e32 v17, v226
	v_readlane_b32 s34, v252, 55
	v_cndmask_b32_e32 v4, v230, v4, vcc
	v_lshlrev_b32_e32 v7, 2, v4
	v_xor_b32_e32 v4, 16, v230
	v_cmp_lt_i32_e32 vcc, v4, v1
	v_ashrrev_i32_e32 v6, 6, v17
	v_lshlrev_b32_e32 v0, 2, v17
	v_cndmask_b32_e32 v4, v230, v4, vcc
	v_lshlrev_b32_e32 v19, 2, v4
	v_xor_b32_e32 v4, 8, v230
	v_cmp_lt_i32_e32 vcc, v4, v1
	v_and_b32_e32 v18, 0xfc, v0
	v_lshl_add_u32 v0, s44, 3, v6
	v_cndmask_b32_e32 v4, v230, v4, vcc
	v_lshlrev_b32_e32 v20, 2, v4
	v_xor_b32_e32 v4, 4, v230
	v_cmp_lt_i32_e32 vcc, v4, v1
	v_add_u32_e32 v8, 0x2000, v0
	v_ashrrev_i32_e32 v9, 31, v8
	v_cndmask_b32_e32 v4, v230, v4, vcc
	v_lshlrev_b32_e32 v21, 2, v4
	v_xor_b32_e32 v4, 2, v230
	v_cmp_lt_i32_e32 vcc, v4, v1
	v_lshlrev_b64 v[10:11], 11, v[8:9]
	v_readlane_b32 s35, v252, 56
	v_cndmask_b32_e32 v4, v230, v4, vcc
	v_lshlrev_b32_e32 v22, 2, v4
	v_xor_b32_e32 v4, 1, v230
	v_cmp_lt_i32_e32 vcc, v4, v1
	v_lshl_add_u64 v[2:3], s[34:35], 0, v[10:11]
	v_lshlrev_b32_e32 v64, 1, v18
	v_cndmask_b32_e32 v1, v230, v4, vcc
	v_lshlrev_b32_e32 v23, 2, v1
	v_ashrrev_i32_e32 v1, 31, v0
	v_lshlrev_b64 v[4:5], 12, v[0:1]
	v_lshl_add_u64 v[0:1], v[2:3], 0, v[64:65]
	s_barrier
	global_load_dwordx2 v[2:3], v[0:1], off
	s_mov_b32 s29, 0x800000
	v_readlane_b32 s48, v251, 0
	v_readlane_b32 s49, v251, 1
	v_readlane_b32 s34, v252, 59
	v_readlane_b32 s35, v252, 60
	v_lshlrev_b32_e32 v16, 12, v6
	v_readlane_b32 s52, v251, 4
	v_lshl_add_u64 v[4:5], s[34:35], 0, v[4:5]
	v_readlane_b32 s53, v251, 5
	v_readlane_b32 s50, v251, 2
	v_readlane_b32 s51, v251, 3
	v_readlane_b32 s54, v251, 6
	v_readlane_b32 s55, v251, 7
	v_readlane_b32 s56, v251, 8
	v_readlane_b32 s57, v251, 9
	v_readlane_b32 s58, v251, 10
	v_readlane_b32 s59, v251, 11
	v_readlane_b32 s60, v251, 12
	v_readlane_b32 s61, v251, 13
	v_readlane_b32 s62, v251, 14
	v_readlane_b32 s63, v251, 15
	global_load_dwordx2 v[144:145], v[0:1], off offset:512
	global_load_dwordx2 v[146:147], v[0:1], off offset:1024
	global_load_dwordx2 v[148:149], v[0:1], off offset:1536
	v_lshlrev_b32_e32 v142, 4, v230
	global_load_dwordx4 v[100:103], v142, s[18:19]
	global_load_dwordx4 v[104:107], v142, s[48:49]
	global_load_dwordx4 v[108:111], v142, s[18:19] offset:1024
	global_load_dwordx4 v[112:115], v142, s[48:49] offset:1024
	global_load_dwordx4 v[116:119], v142, s[18:19] offset:2048
	global_load_dwordx4 v[120:123], v142, s[48:49] offset:2048
	global_load_dwordx4 v[124:127], v142, s[18:19] offset:3072
	global_load_dwordx4 v[128:131], v142, s[48:49] offset:3072
	s_waitcnt vmcnt(0)
	v_lshlrev_b32_e32 v12, 16, v2
	v_and_b32_e32 v13, 0xffff0000, v2
	v_lshlrev_b32_e32 v14, 16, v3
	v_add_f32_e32 v2, v12, v13
	v_and_b32_e32 v15, 0xffff0000, v3
	v_add_f32_e32 v2, v2, v14
	v_add_f32_e32 v2, v2, v15
	v_mov_b32_e32 v3, v2
	s_nop 1
	v_permlane32_swap_b32_e32 v3, v2
	s_waitcnt lgkmcnt(0)
	v_add_f32_e32 v2, v2, v3
	v_mov_b32_e32 v3, v2
	s_nop 1
	v_permlane16_swap_b32_e32 v3, v2
	s_waitcnt lgkmcnt(0)
	v_add_f32_e32 v2, v2, v3
	s_nop 1
	v_mov_b32_dpp v3, v2 row_ror:8 row_mask:0xf bank_mask:0xf
	s_waitcnt lgkmcnt(0)
	v_add_f32_e32 v2, v2, v3
	s_nop 1
	v_mov_b32_dpp v3, v2 row_ror:4 row_mask:0xf bank_mask:0xf
	s_waitcnt lgkmcnt(0)
	v_add_f32_e32 v2, v2, v3
	s_nop 1
	v_mov_b32_dpp v3, v2 quad_perm:[2,3,0,1] row_mask:0xf bank_mask:0xf
	s_waitcnt lgkmcnt(0)
	v_add_f32_e32 v2, v2, v3
	s_nop 1
	v_mov_b32_dpp v3, v2 quad_perm:[1,0,3,2] row_mask:0xf bank_mask:0xf
	s_waitcnt lgkmcnt(0)
	v_add_f32_e32 v2, v2, v3
	v_fmac_f32_e32 v13, 0xbb800000, v2
	v_fmac_f32_e32 v12, 0xbb800000, v2
	v_fmac_f32_e32 v15, 0xbb800000, v2
	v_fmac_f32_e32 v14, 0xbb800000, v2
	v_pk_mul_f32 v[24:25], v[12:13], v[12:13]
	v_pk_mul_f32 v[2:3], v[14:15], v[14:15]
	v_add_f32_e32 v24, v24, v25
	v_add_f32_e32 v2, v2, v24
	v_add_f32_e32 v2, v3, v2
	v_mov_b32_e32 v3, v2
	s_nop 1
	v_permlane32_swap_b32_e32 v3, v2
	s_waitcnt lgkmcnt(0)
	v_add_f32_e32 v2, v2, v3
	v_mov_b32_e32 v3, v2
	s_nop 1
	v_permlane16_swap_b32_e32 v3, v2
	s_waitcnt lgkmcnt(0)
	v_add_f32_e32 v2, v2, v3
	s_nop 1
	v_mov_b32_dpp v3, v2 row_ror:8 row_mask:0xf bank_mask:0xf
	s_waitcnt lgkmcnt(0)
	v_add_f32_e32 v2, v2, v3
	s_nop 1
	v_mov_b32_dpp v3, v2 row_ror:4 row_mask:0xf bank_mask:0xf
	s_waitcnt lgkmcnt(0)
	v_add_f32_e32 v2, v2, v3
	s_nop 1
	v_mov_b32_dpp v3, v2 quad_perm:[2,3,0,1] row_mask:0xf bank_mask:0xf
	s_waitcnt lgkmcnt(0)
	v_add_f32_e32 v2, v2, v3
	s_nop 1
	v_mov_b32_dpp v3, v2 quad_perm:[1,0,3,2] row_mask:0xf bank_mask:0xf
	s_waitcnt lgkmcnt(0)
; #define LAS __attribute__((address_space(3)))
; __device__ __forceinline__ f32x4 unpack4(u32x2 u) { f32x4 r; r[0] = bflo(u[0]); r[1] = bfhi(u[0]); r[2] = bflo(u[1]); r[3] = bfhi(u[1]); return r; }
; __device__ __forceinline__ void mix_sg_sample(const Params& p, LAS unsigned char* lds, int b) {
;     ...
;   for (int g = 0; g < 4; ++g) {
;     const int col = g * 256 + 4 * lane;
;     const f32x4 x = unpack4(*(const u32x2*)(VA + (size_t)(r0 + w) * 1024 + col));
;     const float mean = wave_sum(x[0] + x[1] + x[2] + x[3]) * (1.0f / 256.0f);
;     const f32x4 d = x - mean;
;     const float var = wave_sum(d[0] * d[0] + d[1] * d[1] + d[2] * d[2] + d[3] * d[3]) * (1.0f / 256.0f);
;     const float rstd = rsqrtf(var + LN_EPS);
;     const f32x4 gg = *(const f32x4*)(p.in[7] + col), bb = *(const f32x4*)(p.in[8] + col);
;     const f32x4 va = d * rstd * gg + bb;
;     *(f32x4*)(p.out + O_CV + (size_t)(b * 8 + w) * 1024 + col) = va;
;     *(LAS f32x4*)(vs + w * 1024 + col) = va;
;   }
	v_add_f32_e32 v2, v2, v3
	v_fmamk_f32 v2, v2, 0x3b800000, v228
	v_cmp_gt_f32_e32 vcc, s29, v2
	v_mul_f32_e32 v3, 0x4b800000, v2
	s_nop 0
	v_cndmask_b32_e32 v2, v2, v3, vcc
	v_rsq_f32_e32 v2, v2
	s_nop 0
	v_mul_f32_e32 v3, 0x45800000, v2
	v_cndmask_b32_e32 v32, v2, v3, vcc
	v_lshlrev_b32_e32 v2, 2, v18
	s_nop 1
	v_mov_b64_e32 v[24:25], v[100:101]
	v_mov_b64_e32 v[26:27], v[102:103]
	s_nop 1
	v_mov_b64_e32 v[28:29], v[104:105]
	v_mov_b64_e32 v[30:31], v[106:107]
	v_mov_b32_e32 v3, v65
	v_pk_mul_f32 v[12:13], v[12:13], v[32:33] op_sel_hi:[1,0]
	v_pk_mul_f32 v[14:15], v[14:15], v[32:33] op_sel_hi:[1,0]
	v_lshl_add_u64 v[4:5], v[4:5], 0, v[2:3]
	v_add3_u32 v3, 0, v16, v2
	v_pk_fma_f32 v[14:15], v[26:27], v[14:15], v[30:31]
	v_pk_fma_f32 v[12:13], v[24:25], v[12:13], v[28:29]
	global_store_dwordx4 v[4:5], v[12:15], off
	ds_write_b128 v3, v[12:15]
	s_nop 1
	v_mov_b64_e32 v[14:15], v[144:145]
	v_lshlrev_b32_e32 v12, 16, v14
	v_and_b32_e32 v13, 0xffff0000, v14
	v_lshlrev_b32_e32 v14, 16, v15
	v_add_f32_e32 v16, v12, v13
	v_and_b32_e32 v15, 0xffff0000, v15
	v_add_f32_e32 v16, v16, v14
	v_add_f32_e32 v16, v16, v15
	v_mov_b32_e32 v24, v16
	s_nop 1
	v_permlane32_swap_b32_e32 v24, v16
	s_waitcnt lgkmcnt(0)
	v_add_f32_e32 v16, v16, v24
	v_mov_b32_e32 v24, v16
	s_nop 1
	v_permlane16_swap_b32_e32 v24, v16
	s_waitcnt lgkmcnt(0)
	v_add_f32_e32 v16, v16, v24
	s_nop 1
	v_mov_b32_dpp v24, v16 row_ror:8 row_mask:0xf bank_mask:0xf
	s_waitcnt lgkmcnt(0)
	v_add_f32_e32 v16, v16, v24
	s_nop 1
	v_mov_b32_dpp v24, v16 row_ror:4 row_mask:0xf bank_mask:0xf
	s_waitcnt lgkmcnt(0)
	v_add_f32_e32 v16, v16, v24
	s_nop 1
	v_mov_b32_dpp v24, v16 quad_perm:[2,3,0,1] row_mask:0xf bank_mask:0xf
	s_waitcnt lgkmcnt(0)
	v_add_f32_e32 v16, v16, v24
	s_nop 1
	v_mov_b32_dpp v24, v16 quad_perm:[1,0,3,2] row_mask:0xf bank_mask:0xf
	s_waitcnt lgkmcnt(0)
	v_add_f32_e32 v16, v16, v24
	v_fmac_f32_e32 v13, 0xbb800000, v16
	v_fmac_f32_e32 v12, 0xbb800000, v16
	v_fmac_f32_e32 v15, 0xbb800000, v16
	v_fmac_f32_e32 v14, 0xbb800000, v16
	v_pk_mul_f32 v[26:27], v[12:13], v[12:13]
	v_pk_mul_f32 v[24:25], v[14:15], v[14:15]
	v_add_f32_e32 v16, v26, v27
	v_add_f32_e32 v16, v24, v16
	v_add_f32_e32 v16, v25, v16
	v_mov_b32_e32 v24, v16
	s_nop 1
	v_permlane32_swap_b32_e32 v24, v16
	s_waitcnt lgkmcnt(0)
	v_add_f32_e32 v16, v16, v24
	v_mov_b32_e32 v24, v16
	s_nop 1
	v_permlane16_swap_b32_e32 v24, v16
	s_waitcnt lgkmcnt(0)
	v_add_f32_e32 v16, v16, v24
	s_nop 1
	v_mov_b32_dpp v24, v16 row_ror:8 row_mask:0xf bank_mask:0xf
	s_waitcnt lgkmcnt(0)
	v_add_f32_e32 v16, v16, v24
	s_nop 1
	v_mov_b32_dpp v24, v16 row_ror:4 row_mask:0xf bank_mask:0xf
	s_waitcnt lgkmcnt(0)
	v_add_f32_e32 v16, v16, v24
	s_nop 1
	v_mov_b32_dpp v24, v16 quad_perm:[2,3,0,1] row_mask:0xf bank_mask:0xf
	s_waitcnt lgkmcnt(0)
	v_add_f32_e32 v16, v16, v24
	s_nop 1
	v_mov_b32_dpp v24, v16 quad_perm:[1,0,3,2] row_mask:0xf bank_mask:0xf
	s_waitcnt lgkmcnt(0)
	v_add_f32_e32 v16, v16, v24
	v_fmamk_f32 v16, v16, 0x3b800000, v228
	v_cmp_gt_f32_e32 vcc, s29, v16
	v_mul_f32_e32 v24, 0x4b800000, v16
	s_nop 0
	v_cndmask_b32_e32 v16, v16, v24, vcc
	v_rsq_f32_e32 v16, v16
	s_nop 0
	v_mul_f32_e32 v24, 0x45800000, v16
	v_cndmask_b32_e32 v16, v16, v24, vcc
	s_nop 1
	v_mov_b64_e32 v[24:25], v[108:109]
	v_mov_b64_e32 v[26:27], v[110:111]
	s_nop 1
	v_mov_b64_e32 v[28:29], v[112:113]
	v_mov_b64_e32 v[30:31], v[114:115]
	v_pk_mul_f32 v[12:13], v[12:13], v[16:17] op_sel_hi:[1,0]
	v_pk_mul_f32 v[14:15], v[14:15], v[16:17] op_sel_hi:[1,0]
	v_pk_fma_f32 v[12:13], v[24:25], v[12:13], v[28:29]
	v_pk_fma_f32 v[14:15], v[26:27], v[14:15], v[30:31]
	global_store_dwordx4 v[4:5], v[12:15], off offset:1024
	ds_write_b128 v3, v[12:15] offset:1024
	s_nop 1
	v_mov_b64_e32 v[14:15], v[146:147]
	v_lshlrev_b32_e32 v12, 16, v14
	v_and_b32_e32 v13, 0xffff0000, v14
	v_lshlrev_b32_e32 v14, 16, v15
	v_add_f32_e32 v16, v12, v13
	v_and_b32_e32 v15, 0xffff0000, v15
	v_add_f32_e32 v16, v16, v14
	v_add_f32_e32 v16, v16, v15
	v_mov_b32_e32 v24, v16
	s_nop 1
	v_permlane32_swap_b32_e32 v24, v16
	s_waitcnt lgkmcnt(0)
	v_add_f32_e32 v16, v16, v24
	v_mov_b32_e32 v24, v16
	s_nop 1
	v_permlane16_swap_b32_e32 v24, v16
	s_waitcnt lgkmcnt(0)
	v_add_f32_e32 v16, v16, v24
	s_nop 1
	v_mov_b32_dpp v24, v16 row_ror:8 row_mask:0xf bank_mask:0xf
	s_waitcnt lgkmcnt(0)
	v_add_f32_e32 v16, v16, v24
	s_nop 1
	v_mov_b32_dpp v24, v16 row_ror:4 row_mask:0xf bank_mask:0xf
	s_waitcnt lgkmcnt(0)
	v_add_f32_e32 v16, v16, v24
	s_nop 1
	v_mov_b32_dpp v24, v16 quad_perm:[2,3,0,1] row_mask:0xf bank_mask:0xf
	s_waitcnt lgkmcnt(0)
	v_add_f32_e32 v16, v16, v24
	s_nop 1
	v_mov_b32_dpp v24, v16 quad_perm:[1,0,3,2] row_mask:0xf bank_mask:0xf
	s_waitcnt lgkmcnt(0)
	v_add_f32_e32 v16, v16, v24
	v_fmac_f32_e32 v13, 0xbb800000, v16
	v_fmac_f32_e32 v12, 0xbb800000, v16
	v_fmac_f32_e32 v15, 0xbb800000, v16
	v_fmac_f32_e32 v14, 0xbb800000, v16
	v_pk_mul_f32 v[26:27], v[12:13], v[12:13]
	v_pk_mul_f32 v[24:25], v[14:15], v[14:15]
	v_add_f32_e32 v16, v26, v27
	v_add_f32_e32 v16, v24, v16
	v_add_f32_e32 v16, v25, v16
	v_mov_b32_e32 v24, v16
	s_nop 1
	v_permlane32_swap_b32_e32 v24, v16
	s_waitcnt lgkmcnt(0)
	v_add_f32_e32 v16, v16, v24
	v_mov_b32_e32 v24, v16
	s_nop 1
	v_permlane16_swap_b32_e32 v24, v16
	s_waitcnt lgkmcnt(0)
; #define LAS __attribute__((address_space(3)))
; __device__ __forceinline__ f32x4 unpack4(u32x2 u) { f32x4 r; r[0] = bflo(u[0]); r[1] = bfhi(u[0]); r[2] = bflo(u[1]); r[3] = bfhi(u[1]); return r; }
; __device__ __forceinline__ void mix_sg_sample(const Params& p, LAS unsigned char* lds, int b) {
;     ...
;   for (int g = 0; g < 4; ++g) {
;     const int col = g * 256 + 4 * lane;
;     const f32x4 x = unpack4(*(const u32x2*)(VA + (size_t)(r0 + w) * 1024 + col));
;     const float mean = wave_sum(x[0] + x[1] + x[2] + x[3]) * (1.0f / 256.0f);
;     const f32x4 d = x - mean;
;     const float var = wave_sum(d[0] * d[0] + d[1] * d[1] + d[2] * d[2] + d[3] * d[3]) * (1.0f / 256.0f);
;     const float rstd = rsqrtf(var + LN_EPS);
;     const f32x4 gg = *(const f32x4*)(p.in[7] + col), bb = *(const f32x4*)(p.in[8] + col);
;     const f32x4 va = d * rstd * gg + bb;
;     *(f32x4*)(p.out + O_CV + (size_t)(b * 8 + w) * 1024 + col) = va;
;     *(LAS f32x4*)(vs + w * 1024 + col) = va;
;   }
;   __syncthreads();
; #pragma unroll
;   for (int g = 0; g < 4; ++g) {
;     const int col = g * 256 + 4 * lane;
;     const float bias = p.in[10][g * 128 + w];
;     f32x4 z = (f32x4){bias, bias, bias, bias};
;     for (int j = 0; j <= w; ++j) {
;       const float wv = p.in[9][((size_t)g * 128 + w) * 128 + j];
;       z += *(const LAS f32x4*)(vs + j * 1024 + col) * wv;
	v_add_f32_e32 v16, v16, v24
	s_nop 1
	v_mov_b32_dpp v24, v16 row_ror:8 row_mask:0xf bank_mask:0xf
	s_waitcnt lgkmcnt(0)
	v_add_f32_e32 v16, v16, v24
	s_nop 1
	v_mov_b32_dpp v24, v16 row_ror:4 row_mask:0xf bank_mask:0xf
	s_waitcnt lgkmcnt(0)
	v_add_f32_e32 v16, v16, v24
	s_nop 1
	v_mov_b32_dpp v24, v16 quad_perm:[2,3,0,1] row_mask:0xf bank_mask:0xf
	s_waitcnt lgkmcnt(0)
	v_add_f32_e32 v16, v16, v24
	s_nop 1
	v_mov_b32_dpp v24, v16 quad_perm:[1,0,3,2] row_mask:0xf bank_mask:0xf
	s_waitcnt lgkmcnt(0)
	v_add_f32_e32 v16, v16, v24
	v_fmamk_f32 v16, v16, 0x3b800000, v228
	v_cmp_gt_f32_e32 vcc, s29, v16
	v_mul_f32_e32 v24, 0x4b800000, v16
	s_nop 0
	v_cndmask_b32_e32 v16, v16, v24, vcc
	v_rsq_f32_e32 v16, v16
	s_nop 0
	v_mul_f32_e32 v24, 0x45800000, v16
	v_cndmask_b32_e32 v16, v16, v24, vcc
	s_nop 1
	v_mov_b64_e32 v[24:25], v[116:117]
	v_mov_b64_e32 v[26:27], v[118:119]
	s_nop 1
	v_mov_b64_e32 v[28:29], v[120:121]
	v_mov_b64_e32 v[30:31], v[122:123]
	v_pk_mul_f32 v[12:13], v[12:13], v[16:17] op_sel_hi:[1,0]
	v_pk_mul_f32 v[14:15], v[14:15], v[16:17] op_sel_hi:[1,0]
	v_pk_fma_f32 v[12:13], v[24:25], v[12:13], v[28:29]
	v_pk_fma_f32 v[14:15], v[26:27], v[14:15], v[30:31]
	global_store_dwordx4 v[4:5], v[12:15], off offset:2048
	s_nop 1
	v_mov_b64_e32 v[0:1], v[148:149]
	ds_write_b128 v3, v[12:15] offset:2048
	v_lshlrev_b32_e32 v24, 16, v0
	v_and_b32_e32 v25, 0xffff0000, v0
	v_lshlrev_b32_e32 v0, 16, v1
	v_add_f32_e32 v12, v24, v25
	v_and_b32_e32 v1, 0xffff0000, v1
	v_add_f32_e32 v12, v12, v0
	v_add_f32_e32 v12, v12, v1
	v_mov_b32_e32 v13, v12
	s_nop 1
	v_permlane32_swap_b32_e32 v13, v12
	s_waitcnt lgkmcnt(0)
	v_add_f32_e32 v12, v12, v13
	v_mov_b32_e32 v13, v12
	s_nop 1
	v_permlane16_swap_b32_e32 v13, v12
	s_waitcnt lgkmcnt(0)
	v_add_f32_e32 v12, v12, v13
	s_nop 1
	v_mov_b32_dpp v13, v12 row_ror:8 row_mask:0xf bank_mask:0xf
	s_waitcnt lgkmcnt(0)
	v_add_f32_e32 v12, v12, v13
	s_nop 1
	v_mov_b32_dpp v13, v12 row_ror:4 row_mask:0xf bank_mask:0xf
	s_waitcnt lgkmcnt(0)
	v_add_f32_e32 v12, v12, v13
	s_nop 1
	v_mov_b32_dpp v13, v12 quad_perm:[2,3,0,1] row_mask:0xf bank_mask:0xf
	s_waitcnt lgkmcnt(0)
	v_add_f32_e32 v12, v12, v13
	s_nop 1
	v_mov_b32_dpp v13, v12 quad_perm:[1,0,3,2] row_mask:0xf bank_mask:0xf
	s_waitcnt lgkmcnt(0)
	v_add_f32_e32 v12, v12, v13
	v_fmac_f32_e32 v25, 0xbb800000, v12
	v_fmac_f32_e32 v24, 0xbb800000, v12
	v_fmac_f32_e32 v1, 0xbb800000, v12
	v_fmac_f32_e32 v0, 0xbb800000, v12
	v_pk_mul_f32 v[14:15], v[24:25], v[24:25]
	v_pk_mul_f32 v[12:13], v[0:1], v[0:1]
	v_add_f32_e32 v14, v14, v15
	v_add_f32_e32 v12, v12, v14
	v_add_f32_e32 v12, v13, v12
	v_mov_b32_e32 v7, v12
	s_nop 1
	v_permlane32_swap_b32_e32 v7, v12
	s_waitcnt lgkmcnt(0)
	v_add_f32_e32 v7, v12, v7
	v_mov_b32_e32 v12, v7
	s_nop 1
	v_permlane16_swap_b32_e32 v12, v7
	s_waitcnt lgkmcnt(0)
	v_add_f32_e32 v7, v7, v12
	s_nop 1
	v_mov_b32_dpp v12, v7 row_ror:8 row_mask:0xf bank_mask:0xf
	s_waitcnt lgkmcnt(0)
	v_add_f32_e32 v7, v7, v12
	s_nop 1
	v_mov_b32_dpp v12, v7 row_ror:4 row_mask:0xf bank_mask:0xf
	s_waitcnt lgkmcnt(0)
	v_add_f32_e32 v7, v7, v12
	s_nop 1
	v_mov_b32_dpp v12, v7 quad_perm:[2,3,0,1] row_mask:0xf bank_mask:0xf
	s_waitcnt lgkmcnt(0)
	v_add_f32_e32 v7, v7, v12
	s_nop 1
	v_mov_b32_dpp v12, v7 quad_perm:[1,0,3,2] row_mask:0xf bank_mask:0xf
	s_waitcnt lgkmcnt(0)
	v_add_f32_e32 v7, v7, v12
	v_fmamk_f32 v7, v7, 0x3b800000, v228
	v_cmp_gt_f32_e32 vcc, s29, v7
	v_mul_f32_e32 v12, 0x4b800000, v7
	s_nop 0
	v_cndmask_b32_e32 v7, v7, v12, vcc
	v_rsq_f32_e32 v7, v7
	s_nop 0
	v_mul_f32_e32 v12, 0x45800000, v7
	v_cndmask_b32_e32 v16, v7, v12, vcc
	s_nop 1
	v_mov_b64_e32 v[12:13], v[124:125]
	v_mov_b64_e32 v[14:15], v[126:127]
	s_nop 1
	v_mov_b64_e32 v[20:21], v[128:129]
	v_mov_b64_e32 v[22:23], v[130:131]
	v_pk_mul_f32 v[24:25], v[24:25], v[16:17] op_sel_hi:[1,0]
	v_pk_mul_f32 v[0:1], v[0:1], v[16:17] op_sel_hi:[1,0]
	v_ashrrev_i32_e32 v7, 31, v6
	v_cmp_lt_i32_e32 vcc, -1, v6
	v_add_u32_e32 v16, 1, v6
	v_pk_fma_f32 v[14:15], v[14:15], v[0:1], v[22:23]
	v_pk_fma_f32 v[12:13], v[12:13], v[24:25], v[20:21]
	global_store_dwordx4 v[4:5], v[12:15], off offset:3072
	ds_write_b128 v3, v[12:15] offset:3072
	s_waitcnt lgkmcnt(0)
	v_lshl_add_u64 v[12:13], v[6:7], 2, s[52:53]
	s_barrier
	global_load_dword v0, v[12:13], off
	s_waitcnt vmcnt(0)
	v_mov_b32_e32 v1, v0
	v_mov_b64_e32 v[4:5], v[2:3]
	v_mov_b32_e32 v14, v0
	v_mov_b64_e32 v[2:3], v[0:1]
	s_and_saveexec_b64 s[38:39], vcc
	s_cbranch_execz .LBB0_201
	v_mov_b32_e32 v7, v65
	v_readlane_b32 s48, v251, 0
	v_lshlrev_b64 v[2:3], 9, v[6:7]
	v_readlane_b32 s50, v251, 2
	v_readlane_b32 s51, v251, 3
	v_lshl_add_u32 v4, v18, 2, 0
	v_add_u32_e32 v5, 1, v6
	v_lshl_add_u64 v[2:3], s[50:51], 0, v[2:3]
	s_mov_b64 s[40:41], 0
	v_mov_b32_e32 v1, v0
	v_mov_b32_e32 v14, v0
	v_mov_b32_e32 v15, v0
	v_readlane_b32 s49, v251, 1
	v_readlane_b32 s52, v251, 4
	v_readlane_b32 s53, v251, 5
	v_readlane_b32 s54, v251, 6
	v_readlane_b32 s55, v251, 7
	v_readlane_b32 s56, v251, 8
	v_readlane_b32 s57, v251, 9
	v_readlane_b32 s58, v251, 10
	v_readlane_b32 s59, v251, 11
	v_readlane_b32 s60, v251, 12
	v_readlane_b32 s61, v251, 13
	v_readlane_b32 s62, v251, 14
	v_readlane_b32 s63, v251, 15
